# prep: each wave touches one row of the next half-block of the projected activations (8 x 1 KB dwordx4 into a scratch quad) so the next half-block's 63 narrow loads hit the L2
# speedup vs baseline: 1.0042x; 1.0042x over previous
; __device__ __forceinline__ float bf2f(bf16_t h) { return __uint_as_float(((unsigned)h) << 16); }
; __device__ __forceinline__ void even_prep(const Params& p, int j, LAS unsigned char* lds, const int wave_s) {
;     ...
;             for (int i = 0; i < 10; ++i) { const bf16_t* q = P + ROWC(nh - 2 + i); ur[i] = bf2f(q[2688 + tid]) * bf2f(q[3200 + tid]); }
; #pragma unroll
;             for (int i = 0; i < 9; ++i) { const bf16_t* q = P + ROWC(nh - 1 + i); rr[i] = bf2f(q[tid]); kr[i] = bf2f(q[512 + tid]); vr[i] = bf2f(q[1024 + tid]); }
; #pragma unroll
;             for (int i = 0; i < 8; ++i) { const bf16_t* q = P + ROWC(nh + i); bbv[i] = bf2f(q[2176 + tid]); zbv[i] = bf2f(q[3712 + tid]); }
; #pragma unroll
;             for (int i = 0; i < 8; ++i) { const int n = nh + i;
;                 if (n < n1) {
;                     int b, t, T; const bool samp = n >= NP;
;                     if (!samp) { b = n >> 11; t = n & 2047; T = SEQ; } else { const int s = n - NP; b = s >> 3; t = s & 7; T = ST; }
;                     const float cr = rr[i + 1], ck = kr[i + 1], cv = vr[i + 1];
;                     float qr = rr[i], qk = kr[i], qv = vr[i];
;                     if (t == 0) { qr = 0.f; qk = 0.f; qv = 0.f; if (samp) { qr = sshift[b * ASW + tid]; qk = sshift[b * ASW + 512 + tid]; qv = sshift[b * ASW + 1024 + tid]; } }
;                     const float sr = cr + (qr - cr) * mu_r, sk = ck + (qk - ck) * mu_k, sv = cv + (qv - cv) * mu_v;
;                     const float wp = w0 + DW[(hh * 8 + i) * 64 + lane], ap = a0 + DA[(hh * 8 + i) * 64 + lane];
;                     const float xs = -wp;
;                     const float sp = xs > 20.f ? xs : __logf(1.f + __expf(xs));
;                     const float decay = __expf(-__expf(-sp - 0.5f));
;                     const float a = 1.f / (1.f + __expf(-ap));
;                     const float kk = sk * k_k;
;                     const float ss = wave_sum(kk * kk);
;                     const float kkn = kk * rsqrtf(fmaxf(ss, 1e-24f));
;                     const float kmod = sk * (1.f + (a - 1.f) * k_a);
;                     const float bon = wave_sum(sr * kmod * r_k);
;                     const size_t o = (size_t)n * 512 + tid;
;                     SR[o] = sr; SW[o] = decay; SK[o] = kmod; SV[o] = sv; SKK[o] = kkn; SBB[o] = kkn * a;
;                     if (lane == 0) BON[(size_t)n * 8 + wave] = bon;
.LBB0_1119:
	v_readlane_b32 s100, v253, 53
	v_mbcnt_lo_u32_b32 v238, -1, 0
	v_mbcnt_hi_u32_b32 v238, -1, v238
	v_mul_u32_u24_e32 v238, 14, v238
	s_lshl_b32 s101, s100, 1
	s_lshr_b32 s100, s100, 6
	v_subrev_u32_e32 v238, s101, v238
	s_add_i32 s100, s100, s2
	v_ashrrev_i32_e32 v239, 31, v238
	s_add_i32 s100, s100, 8
	v_lshl_add_u64 v[238:239], v[70:71], 0, v[238:239]
	s_min_i32 s100, s100, 0x40ff
	s_mulk_i32 s100, 0x1100
	s_mov_b32 s101, 0
	v_lshl_add_u64 v[238:239], s[100:101], 1, v[238:239]
	global_load_dwordx4 v[234:237], v[238:239], off
	global_load_dwordx4 v[234:237], v[238:239], off offset:1024
	global_load_dwordx4 v[234:237], v[238:239], off offset:2048
	global_load_dwordx4 v[234:237], v[238:239], off offset:3072
	s_mov_b64 s[100:101], 0x1100
	v_lshl_add_u64 v[238:239], v[238:239], 0, s[100:101]
	global_load_dwordx4 v[234:237], v[238:239], off
	global_load_dwordx4 v[234:237], v[238:239], off offset:1024
	global_load_dwordx4 v[234:237], v[238:239], off offset:2048
	global_load_dwordx4 v[234:237], v[238:239], off offset:3072
	v_lshlrev_b32_e32 v79, 2, v92
	v_lshl_or_b32 v79, s3, 11, v79
	v_readlane_b32 s3, v253, 53
	s_waitcnt vmcnt(46)
	v_lshlrev_b32_e32 v81, 16, v165
	v_lshlrev_b32_e32 v80, 16, v164
	v_add_u32_e32 v86, s3, v79
	ds_read2st64_b32 v[168:169], v86 offset0:64 offset1:80
	s_waitcnt vmcnt(45)
	v_lshlrev_b32_e32 v164, 16, v166
	s_mov_b32 s3, 0x3f317217
	s_waitcnt vmcnt(10)
	v_sub_f32_e32 v76, v76, v80
	s_waitcnt vmcnt(9)
	v_sub_f32_e32 v77, v77, v81
	s_waitcnt lgkmcnt(0)
	v_add_f32_e32 v79, v98, v168
	v_mul_f32_e32 v165, 0xbfb8aa3b, v79
	v_exp_f32_e32 v165, v165
	s_waitcnt vmcnt(8)
	v_sub_f32_e32 v78, v78, v164
	v_fma_f32 v168, v96, v78, v164
	v_mov_b32_e32 v171, 0
	v_add_f32_e32 v165, 1.0, v165
	v_cmp_gt_f32_e32 vcc, s15, v165
	s_nop 1
	v_cndmask_b32_e64 v166, 0, 32, vcc
	v_ldexp_f32 v165, v165, v166
	v_log_f32_e32 v165, v165
	v_fma_f32 v166, v94, v76, v80
	v_fma_f32 v76, v95, v77, v81
	v_add_f32_e32 v77, v99, v169
	v_mul_f32_e32 v167, 0x3f317217, v165
	v_fma_f32 v167, v165, s3, -v167
	v_fmac_f32_e32 v167, 0x3377d1cf, v165
	s_mov_b32 s3, 0x7f800000
	v_fmac_f32_e32 v167, 0x3f317217, v165
	v_cmp_lt_f32_e64 s[44:45], |v165|, s3
	v_mul_f32_e32 v77, 0xbfb8aa3b, v77
	s_mov_b32 s3, 0xc1a00000
	v_cndmask_b32_e64 v165, v165, v167, s[44:45]
	v_cndmask_b32_e32 v167, 0, v222, vcc
	v_exp_f32_e32 v77, v77
	v_sub_f32_e32 v165, v165, v167
	v_cmp_gt_f32_e32 vcc, s3, v79
	v_add_f32_e32 v77, 1.0, v77
	s_nop 0
	v_cndmask_b32_e64 v79, v165, -v79, vcc
	v_sub_f32_e32 v79, -0.5, v79
	v_mul_f32_e32 v79, 0x3fb8aa3b, v79
	v_exp_f32_e32 v79, v79
	v_div_scale_f32 v165, s[44:45], v77, v77, 1.0
	v_rcp_f32_e32 v167, v165
	v_mul_f32_e32 v78, 0xbfb8aa3b, v79
	v_exp_f32_e32 v169, v78
	v_fma_f32 v78, -v165, v167, 1.0
	v_fmac_f32_e32 v167, v78, v167
	v_div_scale_f32 v78, vcc, 1.0, v77, 1.0
	v_mul_f32_e32 v79, v78, v167
	v_fma_f32 v170, -v165, v79, v78
	v_fmac_f32_e32 v79, v170, v167
	v_fma_f32 v78, -v165, v79, v78
	v_mul_f32_e32 v165, v100, v76
	v_mul_f32_e32 v170, v165, v165
	v_div_fmas_f32 v78, v78, v167, v79
	v_div_fixup_f32 v167, v78, v77, 1.0
	v_mov_b32_dpp v170, v170 row_shr:1 row_mask:0xf bank_mask:0xf bound_ctrl:1
	v_fmac_f32_e32 v170, v165, v165
	v_add_f32_e32 v77, -1.0, v167
	v_fma_f32 v77, v101, v77, 1.0
	v_add_f32_dpp v170, v170, v170 row_shr:2 row_mask:0xf bank_mask:0xf bound_ctrl:1
	s_nop 1
	v_add_f32_dpp v170, v170, v170 row_shr:4 row_mask:0xf bank_mask:0xf bound_ctrl:1
	s_nop 1
	v_add_f32_dpp v170, v170, v170 row_shr:8 row_mask:0xf bank_mask:0xf bound_ctrl:1
	s_nop 1
	v_mov_b32_dpp v171, v170 row_bcast:15 row_mask:0xa bank_mask:0xf
	v_add_f32_e32 v170, v170, v171
	v_mov_b32_e32 v171, 0
	s_nop 1
	v_mov_b32_dpp v171, v170 row_bcast:31 row_mask:0xc bank_mask:0xf
	v_add_f32_e32 v170, v170, v171
	s_nop 0
	v_readlane_b32 s3, v170, 63
	s_nop 1
	v_max_f32_e64 v170, s3, s3
	v_max_f32_e32 v170, 0x179abe15, v170
	v_rsq_f32_e32 v170, v170
	s_ashr_i32 s3, s2, 31
	s_lshl_b64 s[44:45], s[2:3], 9
	v_mul_f32_e32 v165, v165, v170
	v_mul_f32_e32 v170, v76, v77
	v_mul_f32_e32 v76, v166, v170
	v_mul_f32_e32 v77, v102, v76
	s_nop 1
	v_mov_b32_dpp v77, v77 row_shr:1 row_mask:0xf bank_mask:0xf bound_ctrl:1
	v_fmac_f32_e32 v77, v102, v76
	s_nop 1
	v_add_f32_dpp v76, v77, v77 row_shr:2 row_mask:0xf bank_mask:0xf bound_ctrl:1
	v_mov_b32_e32 v77, 0
	s_nop 0
	v_add_f32_dpp v76, v76, v76 row_shr:4 row_mask:0xf bank_mask:0xf bound_ctrl:1
	s_nop 1
	v_add_f32_dpp v76, v76, v76 row_shr:8 row_mask:0xf bank_mask:0xf bound_ctrl:1
	s_nop 1
	v_mov_b32_dpp v77, v76 row_bcast:15 row_mask:0xa bank_mask:0xf
	v_add_f32_e32 v76, v76, v77
	v_mov_b32_e32 v77, 0
	s_nop 1
	v_mov_b32_dpp v77, v76 row_bcast:31 row_mask:0xc bank_mask:0xf
	v_add_f32_e32 v76, v76, v77
	s_nop 0
	v_readlane_b32 s31, v76, 63
	v_lshl_add_u64 v[76:77], s[44:45], 0, v[64:65]
	v_lshlrev_b64 v[76:77], 2, v[76:77]
	v_lshl_add_u64 v[78:79], s[58:59], 0, v[76:77]
	global_store_dword v[78:79], v166, off
	v_lshl_add_u64 v[78:79], s[50:51], 0, v[76:77]
	global_store_dword v[78:79], v169, off
	v_lshl_add_u64 v[78:79], s[56:57], 0, v[76:77]
	global_store_dword v[78:79], v170, off
	v_lshl_add_u64 v[78:79], s[52:53], 0, v[76:77]
	global_store_dword v[78:79], v168, off
	v_lshl_add_u64 v[78:79], s[38:39], 0, v[76:77]
	global_store_dword v[78:79], v165, off
	v_mul_f32_e32 v78, v167, v165
	v_lshl_add_u64 v[76:77], s[54:55], 0, v[76:77]
	global_store_dword v[76:77], v78, off
	s_and_saveexec_b64 s[44:45], s[40:41]
	s_cbranch_execz .LBB0_1121
	s_lshl_b64 vcc, s[2:3], 5
	s_add_u32 vcc_lo, s17, vcc_lo
	s_addc_u32 vcc_hi, s83, vcc_hi
	v_mov_b32_e32 v76, s31
	global_store_dword v185, v76, vcc
